# in-proj epilogue stores write-through (sc1) so the barrier L2 writeback is cheap; flat-release barrier; lru conv de-serialised
# speedup vs baseline: 1.0611x; 1.0031x over previous
.LBB0_231:
	s_lshl_b32 s6, s6, 8
	v_lshrrev_b32_e32 v145, 1, v146
	v_and_or_b32 v145, v145, 24, s6
	v_or_b32_e32 v146, s52, v145
	v_ashrrev_i32_e32 v147, 31, v146
	v_lshl_add_u64 v[146:147], v[146:147], 1, s[36:37]
	v_lshl_add_u64 v[146:147], v[146:147], 0, s[14:15]
	v_mov_b32_e32 v228, v150
	v_pk_mul_f32 v[126:127], v[126:127], v[150:151] op_sel_hi:[1,0]
	v_pk_mul_f32 v[124:125], v[124:125], v[150:151] op_sel_hi:[1,0]
	v_pk_mul_f32 v[160:161], v[122:123], v[150:151] op_sel_hi:[1,0]
	v_pk_mul_f32 v[122:123], v[120:121], v[150:151] op_sel_hi:[1,0]
	v_mad_i64_i32 v[158:159], s[6:7], v144, s60, v[146:147]
	v_cvt_pk_bf16_f32 v120, v124, v125
	v_cvt_pk_bf16_f32 v121, v126, v127
	v_cvt_pk_bf16_f32 v122, v122, v123
	v_cvt_pk_bf16_f32 v123, v160, v161
	global_store_dwordx4 v[158:159], v[120:123], off sc1
	v_pk_mul_f32 v[118:119], v[118:119], v[150:151] op_sel_hi:[1,0]
	v_pk_mul_f32 v[116:117], v[116:117], v[150:151] op_sel_hi:[1,0]
	v_pk_mul_f32 v[120:121], v[114:115], v[150:151] op_sel_hi:[1,0]
	v_pk_mul_f32 v[114:115], v[112:113], v[150:151] op_sel_hi:[1,0]
	v_cvt_pk_bf16_f32 v112, v116, v117
	v_cvt_pk_bf16_f32 v113, v118, v119
	v_cvt_pk_bf16_f32 v114, v114, v115
	v_cvt_pk_bf16_f32 v115, v120, v121
	global_store_dwordx4 v[158:159], v[112:115], off offset:256 sc1
	s_andn2_b64 vcc, exec, s[34:35]
	s_nop 0
	v_or_b32_e32 v112, 16, v144
	v_cndmask_b32_e64 v113, 0, 1, s[34:35]
	v_cmp_ne_u32_e64 s[6:7], 1, v113
	v_ashrrev_i32_e32 v113, 31, v112
	s_cbranch_vccnz .LBB0_233
	v_lshl_add_u64 v[114:115], v[112:113], 2, s[30:31]
	global_load_dword v113, v[114:115], off
	s_waitcnt vmcnt(0)
	v_fmamk_f32 v113, v113, 0x3a800000, v156
	v_rsq_f32_e32 v148, v113
.LBB0_233:
	s_nop 0
	v_mov_b32_e32 v229, v148
	v_pk_mul_f32 v[110:111], v[110:111], v[148:149] op_sel_hi:[1,0]
	v_pk_mul_f32 v[108:109], v[108:109], v[148:149] op_sel_hi:[1,0]
	v_pk_mul_f32 v[114:115], v[106:107], v[148:149] op_sel_hi:[1,0]
	v_pk_mul_f32 v[106:107], v[104:105], v[148:149] op_sel_hi:[1,0]
	v_mad_i64_i32 v[112:113], s[34:35], v112, s60, v[146:147]
	v_cvt_pk_bf16_f32 v104, v108, v109
	v_cvt_pk_bf16_f32 v105, v110, v111
	v_cvt_pk_bf16_f32 v106, v106, v107
	v_cvt_pk_bf16_f32 v107, v114, v115
	global_store_dwordx4 v[112:113], v[104:107], off sc1
	v_pk_mul_f32 v[102:103], v[102:103], v[148:149] op_sel_hi:[1,0]
	v_pk_mul_f32 v[100:101], v[100:101], v[148:149] op_sel_hi:[1,0]
	v_pk_mul_f32 v[104:105], v[98:99], v[148:149] op_sel_hi:[1,0]
	v_pk_mul_f32 v[98:99], v[96:97], v[148:149] op_sel_hi:[1,0]
	v_cvt_pk_bf16_f32 v96, v100, v101
	v_cvt_pk_bf16_f32 v97, v102, v103
	v_cvt_pk_bf16_f32 v98, v98, v99
	v_cvt_pk_bf16_f32 v99, v104, v105
	v_or_b32_e32 v100, 32, v144
	global_store_dwordx4 v[112:113], v[96:99], off offset:256 sc1
	v_ashrrev_i32_e32 v101, 31, v100
	s_and_b64 vcc, exec, s[6:7]
	v_mov_b32_e32 v96, 1.0
	v_mov_b32_e32 v98, 1.0
	s_cbranch_vccnz .LBB0_235
	v_lshl_add_u64 v[98:99], v[100:101], 2, s[30:31]
	global_load_dword v97, v[98:99], off
	s_waitcnt vmcnt(0)
	v_fmamk_f32 v97, v97, 0x3a800000, v156
	v_rsq_f32_e32 v98, v97
.LBB0_235:
	s_nop 0
	v_mov_b32_e32 v230, v98
	v_pk_mul_f32 v[94:95], v[94:95], v[98:99] op_sel_hi:[1,0]
	v_pk_mul_f32 v[92:93], v[92:93], v[98:99] op_sel_hi:[1,0]
	v_pk_mul_f32 v[102:103], v[90:91], v[98:99] op_sel_hi:[1,0]
	v_pk_mul_f32 v[90:91], v[88:89], v[98:99] op_sel_hi:[1,0]
	v_mad_i64_i32 v[100:101], s[34:35], v100, s60, v[146:147]
	v_cvt_pk_bf16_f32 v88, v92, v93
	v_cvt_pk_bf16_f32 v89, v94, v95
	v_cvt_pk_bf16_f32 v90, v90, v91
	v_cvt_pk_bf16_f32 v91, v102, v103
	global_store_dwordx4 v[100:101], v[88:91], off sc1
	v_pk_mul_f32 v[86:87], v[86:87], v[98:99] op_sel_hi:[1,0]
	v_pk_mul_f32 v[84:85], v[84:85], v[98:99] op_sel_hi:[1,0]
	v_pk_mul_f32 v[88:89], v[82:83], v[98:99] op_sel_hi:[1,0]
	v_pk_mul_f32 v[82:83], v[80:81], v[98:99] op_sel_hi:[1,0]
	v_cvt_pk_bf16_f32 v80, v84, v85
	v_cvt_pk_bf16_f32 v81, v86, v87
	v_cvt_pk_bf16_f32 v82, v82, v83
	v_cvt_pk_bf16_f32 v83, v88, v89
	global_store_dwordx4 v[100:101], v[80:83], off offset:256 sc1
	s_and_b64 vcc, exec, s[6:7]
	s_nop 0
	v_or_b32_e32 v80, 48, v144
	v_ashrrev_i32_e32 v81, 31, v80
	s_cbranch_vccnz .LBB0_237
	v_lshl_add_u64 v[82:83], v[80:81], 2, s[30:31]
	global_load_dword v81, v[82:83], off
	s_waitcnt vmcnt(0)
	v_fmamk_f32 v81, v81, 0x3a800000, v156
	v_rsq_f32_e32 v96, v81
.LBB0_237:
	s_nop 0
	v_mov_b32_e32 v231, v96
	v_pk_mul_f32 v[78:79], v[78:79], v[96:97] op_sel_hi:[1,0]
	v_pk_mul_f32 v[76:77], v[76:77], v[96:97] op_sel_hi:[1,0]
	v_pk_mul_f32 v[82:83], v[74:75], v[96:97] op_sel_hi:[1,0]
	v_pk_mul_f32 v[74:75], v[72:73], v[96:97] op_sel_hi:[1,0]
	v_mad_i64_i32 v[80:81], s[34:35], v80, s60, v[146:147]
	v_cvt_pk_bf16_f32 v72, v76, v77
	v_cvt_pk_bf16_f32 v73, v78, v79
	v_cvt_pk_bf16_f32 v74, v74, v75
	v_cvt_pk_bf16_f32 v75, v82, v83
	global_store_dwordx4 v[80:81], v[72:75], off sc1
	v_pk_mul_f32 v[70:71], v[70:71], v[96:97] op_sel_hi:[1,0]
	v_pk_mul_f32 v[68:69], v[68:69], v[96:97] op_sel_hi:[1,0]
	v_pk_mul_f32 v[72:73], v[66:67], v[96:97] op_sel_hi:[1,0]
	v_pk_mul_f32 v[66:67], v[64:65], v[96:97] op_sel_hi:[1,0]
	v_cvt_pk_bf16_f32 v64, v68, v69
	v_cvt_pk_bf16_f32 v65, v70, v71
	v_cvt_pk_bf16_f32 v66, v66, v67
	v_cvt_pk_bf16_f32 v67, v72, v73
	v_add_u32_e32 v68, 0x80, v144
	global_store_dwordx4 v[80:81], v[64:67], off offset:256 sc1
	v_ashrrev_i32_e32 v69, 31, v68
	s_and_b64 vcc, exec, s[6:7]
	v_mov_b32_e32 v64, 1.0
	v_mov_b32_e32 v66, 1.0
	s_cbranch_vccnz .LBB0_239
	v_lshl_add_u64 v[66:67], v[68:69], 2, s[30:31]
	global_load_dword v65, v[66:67], off
	s_waitcnt vmcnt(0)
	v_fmamk_f32 v65, v65, 0x3a800000, v156
	v_rsq_f32_e32 v66, v65
.LBB0_239:
	s_nop 0
	v_mov_b32_e32 v232, v66
	v_pk_mul_f32 v[62:63], v[62:63], v[66:67] op_sel_hi:[1,0]
	v_pk_mul_f32 v[60:61], v[60:61], v[66:67] op_sel_hi:[1,0]
	v_pk_mul_f32 v[70:71], v[58:59], v[66:67] op_sel_hi:[1,0]
	v_pk_mul_f32 v[58:59], v[56:57], v[66:67] op_sel_hi:[1,0]
	v_mad_i64_i32 v[68:69], s[34:35], v68, s60, v[146:147]
	v_cvt_pk_bf16_f32 v56, v60, v61
	v_cvt_pk_bf16_f32 v57, v62, v63
	v_cvt_pk_bf16_f32 v58, v58, v59
	v_cvt_pk_bf16_f32 v59, v70, v71
	global_store_dwordx4 v[68:69], v[56:59], off sc1
	v_pk_mul_f32 v[54:55], v[54:55], v[66:67] op_sel_hi:[1,0]
	v_pk_mul_f32 v[52:53], v[52:53], v[66:67] op_sel_hi:[1,0]
	v_pk_mul_f32 v[56:57], v[50:51], v[66:67] op_sel_hi:[1,0]
	v_pk_mul_f32 v[50:51], v[48:49], v[66:67] op_sel_hi:[1,0]
	v_cvt_pk_bf16_f32 v48, v52, v53
	v_cvt_pk_bf16_f32 v49, v54, v55
	v_cvt_pk_bf16_f32 v50, v50, v51
	v_cvt_pk_bf16_f32 v51, v56, v57
	global_store_dwordx4 v[68:69], v[48:51], off offset:256 sc1
	s_and_b64 vcc, exec, s[6:7]
	s_nop 0
	v_add_u32_e32 v48, 0x90, v144
	v_ashrrev_i32_e32 v49, 31, v48
	s_cbranch_vccnz .LBB0_241
	v_lshl_add_u64 v[50:51], v[48:49], 2, s[30:31]
	global_load_dword v49, v[50:51], off
	s_waitcnt vmcnt(0)
	v_fmamk_f32 v49, v49, 0x3a800000, v156
	v_rsq_f32_e32 v64, v49
.LBB0_241:
	s_nop 0
	v_mov_b32_e32 v233, v64
	v_pk_mul_f32 v[46:47], v[46:47], v[64:65] op_sel_hi:[1,0]
	v_pk_mul_f32 v[44:45], v[44:45], v[64:65] op_sel_hi:[1,0]
	v_pk_mul_f32 v[50:51], v[42:43], v[64:65] op_sel_hi:[1,0]
	v_pk_mul_f32 v[42:43], v[40:41], v[64:65] op_sel_hi:[1,0]
	v_mad_i64_i32 v[48:49], s[34:35], v48, s60, v[146:147]
	v_cvt_pk_bf16_f32 v40, v44, v45
	v_cvt_pk_bf16_f32 v41, v46, v47
	v_cvt_pk_bf16_f32 v42, v42, v43
	v_cvt_pk_bf16_f32 v43, v50, v51
	global_store_dwordx4 v[48:49], v[40:43], off sc1
	v_pk_mul_f32 v[38:39], v[38:39], v[64:65] op_sel_hi:[1,0]
	v_pk_mul_f32 v[36:37], v[36:37], v[64:65] op_sel_hi:[1,0]
	v_pk_mul_f32 v[40:41], v[34:35], v[64:65] op_sel_hi:[1,0]
	v_pk_mul_f32 v[34:35], v[32:33], v[64:65] op_sel_hi:[1,0]
	v_cvt_pk_bf16_f32 v32, v36, v37
	v_cvt_pk_bf16_f32 v33, v38, v39
	v_cvt_pk_bf16_f32 v34, v34, v35
	v_cvt_pk_bf16_f32 v35, v40, v41
	v_add_u32_e32 v36, 0xa0, v144
	global_store_dwordx4 v[48:49], v[32:35], off offset:256 sc1
	v_ashrrev_i32_e32 v37, 31, v36
	s_and_b64 vcc, exec, s[6:7]
	v_mov_b32_e32 v32, 1.0
	v_mov_b32_e32 v34, 1.0
	s_cbranch_vccnz .LBB0_243
	v_lshl_add_u64 v[34:35], v[36:37], 2, s[30:31]
	global_load_dword v33, v[34:35], off
	s_waitcnt vmcnt(0)
	v_fmamk_f32 v33, v33, 0x3a800000, v156
	v_rsq_f32_e32 v34, v33
.LBB0_243:
	s_nop 0
	v_mov_b32_e32 v234, v34
	v_pk_mul_f32 v[30:31], v[30:31], v[34:35] op_sel_hi:[1,0]
	v_pk_mul_f32 v[28:29], v[28:29], v[34:35] op_sel_hi:[1,0]
	v_pk_mul_f32 v[38:39], v[26:27], v[34:35] op_sel_hi:[1,0]
	v_pk_mul_f32 v[26:27], v[24:25], v[34:35] op_sel_hi:[1,0]
	v_mad_i64_i32 v[36:37], s[34:35], v36, s60, v[146:147]
	v_cvt_pk_bf16_f32 v24, v28, v29
	v_cvt_pk_bf16_f32 v25, v30, v31
	v_cvt_pk_bf16_f32 v26, v26, v27
	v_cvt_pk_bf16_f32 v27, v38, v39
	global_store_dwordx4 v[36:37], v[24:27], off sc1
	v_pk_mul_f32 v[22:23], v[22:23], v[34:35] op_sel_hi:[1,0]
	v_pk_mul_f32 v[20:21], v[20:21], v[34:35] op_sel_hi:[1,0]
	v_pk_mul_f32 v[24:25], v[18:19], v[34:35] op_sel_hi:[1,0]
	v_pk_mul_f32 v[18:19], v[16:17], v[34:35] op_sel_hi:[1,0]
	v_cvt_pk_bf16_f32 v16, v20, v21
	v_cvt_pk_bf16_f32 v17, v22, v23
	v_cvt_pk_bf16_f32 v18, v18, v19
	v_cvt_pk_bf16_f32 v19, v24, v25
	global_store_dwordx4 v[36:37], v[16:19], off offset:256 sc1
	s_and_b64 vcc, exec, s[6:7]
	s_nop 0
	v_add_u32_e32 v16, 0xb0, v144
	v_ashrrev_i32_e32 v17, 31, v16
	s_cbranch_vccnz .LBB0_245
	v_lshl_add_u64 v[18:19], v[16:17], 2, s[30:31]
	global_load_dword v17, v[18:19], off
	s_waitcnt vmcnt(0)
	v_fmamk_f32 v17, v17, 0x3a800000, v156
	v_rsq_f32_e32 v32, v17
.LBB0_245:
	s_nop 0
	v_mov_b32_e32 v235, v32
	v_pk_mul_f32 v[14:15], v[14:15], v[32:33] op_sel_hi:[1,0]
	v_pk_mul_f32 v[12:13], v[12:13], v[32:33] op_sel_hi:[1,0]
	v_pk_mul_f32 v[18:19], v[10:11], v[32:33] op_sel_hi:[1,0]
	v_pk_mul_f32 v[10:11], v[8:9], v[32:33] op_sel_hi:[1,0]
	v_mad_i64_i32 v[16:17], s[6:7], v16, s60, v[146:147]
	v_cvt_pk_bf16_f32 v8, v12, v13
	v_cvt_pk_bf16_f32 v9, v14, v15
	v_cvt_pk_bf16_f32 v10, v10, v11
	v_cvt_pk_bf16_f32 v11, v18, v19
	global_store_dwordx4 v[16:17], v[8:11], off sc1
	v_pk_mul_f32 v[6:7], v[6:7], v[32:33] op_sel_hi:[1,0]
	v_pk_mul_f32 v[4:5], v[4:5], v[32:33] op_sel_hi:[1,0]
	v_pk_mul_f32 v[8:9], v[2:3], v[32:33] op_sel_hi:[1,0]
	v_pk_mul_f32 v[2:3], v[0:1], v[32:33] op_sel_hi:[1,0]
	v_cvt_pk_bf16_f32 v0, v4, v5
	v_cvt_pk_bf16_f32 v1, v6, v7
	v_cvt_pk_bf16_f32 v2, v2, v3
	v_cvt_pk_bf16_f32 v3, v8, v9
	s_andn2_b64 vcc, exec, s[4:5]
	s_mov_b64 s[4:5], -1
	global_store_dwordx4 v[16:17], v[0:3], off offset:256 sc1
	s_cbranch_vccnz .LBB0_222

.Lip0_fast:
	s_andn2_b64 vcc, exec, s[4:5]
	s_load_dwordx2 s[36:37], s[0:1], 0x138
	s_mov_b32 s94, 0x16000
	s_mov_b32 s95, 0
	s_mov_b32 s96, 0x6e000
	s_mov_b32 s97, 0
	v_and_or_b32 v146, v154, 15, s51
	v_lshl_add_u32 v146, s30, 8, v146
	s_lshl_b32 s101, s6, 8
	v_lshrrev_b32_e32 v144, 1, v154
	v_and_or_b32 v144, v144, 24, s101
	v_or_b32_e32 v144, s52, v144
	v_ashrrev_i32_e32 v145, 31, v144
	s_waitcnt lgkmcnt(0)
	v_lshl_add_u64 v[144:145], v[144:145], 1, s[36:37]
	v_lshl_add_u64 v[144:145], v[144:145], 0, s[14:15]
	v_mad_i64_i32 v[144:145], s[36:37], v146, s60, v[144:145]
	v_pk_mul_f32 v[124:125], v[124:125], v[228:229] op_sel_hi:[1,0]
	v_pk_mul_f32 v[126:127], v[126:127], v[228:229] op_sel_hi:[1,0]
	v_pk_mul_f32 v[120:121], v[120:121], v[228:229] op_sel_hi:[1,0]
	v_pk_mul_f32 v[122:123], v[122:123], v[228:229] op_sel_hi:[1,0]
	v_cvt_pk_bf16_f32 v156, v124, v125
	v_cvt_pk_bf16_f32 v157, v126, v127
	v_cvt_pk_bf16_f32 v158, v120, v121
	v_cvt_pk_bf16_f32 v159, v122, v123
	global_store_dwordx4 v[144:145], v[156:159], off sc1
	v_pk_mul_f32 v[116:117], v[116:117], v[228:229] op_sel_hi:[1,0]
	v_pk_mul_f32 v[118:119], v[118:119], v[228:229] op_sel_hi:[1,0]
	v_pk_mul_f32 v[112:113], v[112:113], v[228:229] op_sel_hi:[1,0]
	v_pk_mul_f32 v[114:115], v[114:115], v[228:229] op_sel_hi:[1,0]
	v_cvt_pk_bf16_f32 v160, v116, v117
	v_cvt_pk_bf16_f32 v161, v118, v119
	v_cvt_pk_bf16_f32 v162, v112, v113
	v_cvt_pk_bf16_f32 v163, v114, v115
	global_store_dwordx4 v[144:145], v[160:163], off offset:256 sc1
	v_lshl_add_u64 v[144:145], v[144:145], 0, s[94:95]
	v_pk_mul_f32 v[108:109], v[108:109], v[228:229] op_sel:[0,1] op_sel_hi:[1,1]
	v_pk_mul_f32 v[110:111], v[110:111], v[228:229] op_sel:[0,1] op_sel_hi:[1,1]
	v_pk_mul_f32 v[104:105], v[104:105], v[228:229] op_sel:[0,1] op_sel_hi:[1,1]
	v_pk_mul_f32 v[106:107], v[106:107], v[228:229] op_sel:[0,1] op_sel_hi:[1,1]
	v_cvt_pk_bf16_f32 v156, v108, v109
	v_cvt_pk_bf16_f32 v157, v110, v111
	v_cvt_pk_bf16_f32 v158, v104, v105
	v_cvt_pk_bf16_f32 v159, v106, v107
	global_store_dwordx4 v[144:145], v[156:159], off sc1
	v_pk_mul_f32 v[100:101], v[100:101], v[228:229] op_sel:[0,1] op_sel_hi:[1,1]
	v_pk_mul_f32 v[102:103], v[102:103], v[228:229] op_sel:[0,1] op_sel_hi:[1,1]
	v_pk_mul_f32 v[96:97], v[96:97], v[228:229] op_sel:[0,1] op_sel_hi:[1,1]
	v_pk_mul_f32 v[98:99], v[98:99], v[228:229] op_sel:[0,1] op_sel_hi:[1,1]
	v_cvt_pk_bf16_f32 v160, v100, v101
	v_cvt_pk_bf16_f32 v161, v102, v103
	v_cvt_pk_bf16_f32 v162, v96, v97
	v_cvt_pk_bf16_f32 v163, v98, v99
	global_store_dwordx4 v[144:145], v[160:163], off offset:256 sc1
	v_lshl_add_u64 v[144:145], v[144:145], 0, s[94:95]
	v_pk_mul_f32 v[92:93], v[92:93], v[230:231] op_sel_hi:[1,0]
	v_pk_mul_f32 v[94:95], v[94:95], v[230:231] op_sel_hi:[1,0]
	v_pk_mul_f32 v[88:89], v[88:89], v[230:231] op_sel_hi:[1,0]
	v_pk_mul_f32 v[90:91], v[90:91], v[230:231] op_sel_hi:[1,0]
	v_cvt_pk_bf16_f32 v156, v92, v93
	v_cvt_pk_bf16_f32 v157, v94, v95
	v_cvt_pk_bf16_f32 v158, v88, v89
	v_cvt_pk_bf16_f32 v159, v90, v91
	global_store_dwordx4 v[144:145], v[156:159], off sc1
	v_pk_mul_f32 v[84:85], v[84:85], v[230:231] op_sel_hi:[1,0]
	v_pk_mul_f32 v[86:87], v[86:87], v[230:231] op_sel_hi:[1,0]
	v_pk_mul_f32 v[80:81], v[80:81], v[230:231] op_sel_hi:[1,0]
	v_pk_mul_f32 v[82:83], v[82:83], v[230:231] op_sel_hi:[1,0]
	v_cvt_pk_bf16_f32 v160, v84, v85
	v_cvt_pk_bf16_f32 v161, v86, v87
	v_cvt_pk_bf16_f32 v162, v80, v81
	v_cvt_pk_bf16_f32 v163, v82, v83
	global_store_dwordx4 v[144:145], v[160:163], off offset:256 sc1
	v_lshl_add_u64 v[144:145], v[144:145], 0, s[94:95]
	v_pk_mul_f32 v[76:77], v[76:77], v[230:231] op_sel:[0,1] op_sel_hi:[1,1]
	v_pk_mul_f32 v[78:79], v[78:79], v[230:231] op_sel:[0,1] op_sel_hi:[1,1]
	v_pk_mul_f32 v[72:73], v[72:73], v[230:231] op_sel:[0,1] op_sel_hi:[1,1]
	v_pk_mul_f32 v[74:75], v[74:75], v[230:231] op_sel:[0,1] op_sel_hi:[1,1]
	v_cvt_pk_bf16_f32 v156, v76, v77
	v_cvt_pk_bf16_f32 v157, v78, v79
	v_cvt_pk_bf16_f32 v158, v72, v73
	v_cvt_pk_bf16_f32 v159, v74, v75
	global_store_dwordx4 v[144:145], v[156:159], off sc1
	v_pk_mul_f32 v[68:69], v[68:69], v[230:231] op_sel:[0,1] op_sel_hi:[1,1]
	v_pk_mul_f32 v[70:71], v[70:71], v[230:231] op_sel:[0,1] op_sel_hi:[1,1]
	v_pk_mul_f32 v[64:65], v[64:65], v[230:231] op_sel:[0,1] op_sel_hi:[1,1]
	v_pk_mul_f32 v[66:67], v[66:67], v[230:231] op_sel:[0,1] op_sel_hi:[1,1]
	v_cvt_pk_bf16_f32 v160, v68, v69
	v_cvt_pk_bf16_f32 v161, v70, v71
	v_cvt_pk_bf16_f32 v162, v64, v65
	v_cvt_pk_bf16_f32 v163, v66, v67
	global_store_dwordx4 v[144:145], v[160:163], off offset:256 sc1
	v_lshl_add_u64 v[144:145], v[144:145], 0, s[96:97]
	v_pk_mul_f32 v[60:61], v[60:61], v[232:233] op_sel_hi:[1,0]
	v_pk_mul_f32 v[62:63], v[62:63], v[232:233] op_sel_hi:[1,0]
	v_pk_mul_f32 v[56:57], v[56:57], v[232:233] op_sel_hi:[1,0]
	v_pk_mul_f32 v[58:59], v[58:59], v[232:233] op_sel_hi:[1,0]
	v_cvt_pk_bf16_f32 v156, v60, v61
	v_cvt_pk_bf16_f32 v157, v62, v63
	v_cvt_pk_bf16_f32 v158, v56, v57
	v_cvt_pk_bf16_f32 v159, v58, v59
	global_store_dwordx4 v[144:145], v[156:159], off sc1
	v_pk_mul_f32 v[52:53], v[52:53], v[232:233] op_sel_hi:[1,0]
	v_pk_mul_f32 v[54:55], v[54:55], v[232:233] op_sel_hi:[1,0]
	v_pk_mul_f32 v[48:49], v[48:49], v[232:233] op_sel_hi:[1,0]
	v_pk_mul_f32 v[50:51], v[50:51], v[232:233] op_sel_hi:[1,0]
	v_cvt_pk_bf16_f32 v160, v52, v53
	v_cvt_pk_bf16_f32 v161, v54, v55
	v_cvt_pk_bf16_f32 v162, v48, v49
	v_cvt_pk_bf16_f32 v163, v50, v51
	global_store_dwordx4 v[144:145], v[160:163], off offset:256 sc1
	v_lshl_add_u64 v[144:145], v[144:145], 0, s[94:95]
	v_pk_mul_f32 v[44:45], v[44:45], v[232:233] op_sel:[0,1] op_sel_hi:[1,1]
	v_pk_mul_f32 v[46:47], v[46:47], v[232:233] op_sel:[0,1] op_sel_hi:[1,1]
	v_pk_mul_f32 v[40:41], v[40:41], v[232:233] op_sel:[0,1] op_sel_hi:[1,1]
	v_pk_mul_f32 v[42:43], v[42:43], v[232:233] op_sel:[0,1] op_sel_hi:[1,1]
	v_cvt_pk_bf16_f32 v156, v44, v45
	v_cvt_pk_bf16_f32 v157, v46, v47
	v_cvt_pk_bf16_f32 v158, v40, v41
	v_cvt_pk_bf16_f32 v159, v42, v43
	global_store_dwordx4 v[144:145], v[156:159], off sc1
	v_pk_mul_f32 v[36:37], v[36:37], v[232:233] op_sel:[0,1] op_sel_hi:[1,1]
	v_pk_mul_f32 v[38:39], v[38:39], v[232:233] op_sel:[0,1] op_sel_hi:[1,1]
	v_pk_mul_f32 v[32:33], v[32:33], v[232:233] op_sel:[0,1] op_sel_hi:[1,1]
	v_pk_mul_f32 v[34:35], v[34:35], v[232:233] op_sel:[0,1] op_sel_hi:[1,1]
	v_cvt_pk_bf16_f32 v160, v36, v37
	v_cvt_pk_bf16_f32 v161, v38, v39
	v_cvt_pk_bf16_f32 v162, v32, v33
	v_cvt_pk_bf16_f32 v163, v34, v35
	global_store_dwordx4 v[144:145], v[160:163], off offset:256 sc1
	v_lshl_add_u64 v[144:145], v[144:145], 0, s[94:95]
	v_pk_mul_f32 v[28:29], v[28:29], v[234:235] op_sel_hi:[1,0]
	v_pk_mul_f32 v[30:31], v[30:31], v[234:235] op_sel_hi:[1,0]
	v_pk_mul_f32 v[24:25], v[24:25], v[234:235] op_sel_hi:[1,0]
	v_pk_mul_f32 v[26:27], v[26:27], v[234:235] op_sel_hi:[1,0]
	v_cvt_pk_bf16_f32 v156, v28, v29
	v_cvt_pk_bf16_f32 v157, v30, v31
	v_cvt_pk_bf16_f32 v158, v24, v25
	v_cvt_pk_bf16_f32 v159, v26, v27
	global_store_dwordx4 v[144:145], v[156:159], off sc1
	v_pk_mul_f32 v[20:21], v[20:21], v[234:235] op_sel_hi:[1,0]
	v_pk_mul_f32 v[22:23], v[22:23], v[234:235] op_sel_hi:[1,0]
	v_pk_mul_f32 v[16:17], v[16:17], v[234:235] op_sel_hi:[1,0]
	v_pk_mul_f32 v[18:19], v[18:19], v[234:235] op_sel_hi:[1,0]
	v_cvt_pk_bf16_f32 v160, v20, v21
	v_cvt_pk_bf16_f32 v161, v22, v23
	v_cvt_pk_bf16_f32 v162, v16, v17
	v_cvt_pk_bf16_f32 v163, v18, v19
	global_store_dwordx4 v[144:145], v[160:163], off offset:256 sc1
	v_lshl_add_u64 v[144:145], v[144:145], 0, s[94:95]
	v_pk_mul_f32 v[12:13], v[12:13], v[234:235] op_sel:[0,1] op_sel_hi:[1,1]
	v_pk_mul_f32 v[14:15], v[14:15], v[234:235] op_sel:[0,1] op_sel_hi:[1,1]
	v_pk_mul_f32 v[8:9], v[8:9], v[234:235] op_sel:[0,1] op_sel_hi:[1,1]
	v_pk_mul_f32 v[10:11], v[10:11], v[234:235] op_sel:[0,1] op_sel_hi:[1,1]
	v_cvt_pk_bf16_f32 v156, v12, v13
	v_cvt_pk_bf16_f32 v157, v14, v15
	v_cvt_pk_bf16_f32 v158, v8, v9
	v_cvt_pk_bf16_f32 v159, v10, v11
	global_store_dwordx4 v[144:145], v[156:159], off sc1
	v_pk_mul_f32 v[4:5], v[4:5], v[234:235] op_sel:[0,1] op_sel_hi:[1,1]
	v_pk_mul_f32 v[6:7], v[6:7], v[234:235] op_sel:[0,1] op_sel_hi:[1,1]
	v_pk_mul_f32 v[0:1], v[0:1], v[234:235] op_sel:[0,1] op_sel_hi:[1,1]
	v_pk_mul_f32 v[2:3], v[2:3], v[234:235] op_sel:[0,1] op_sel_hi:[1,1]
	v_cvt_pk_bf16_f32 v160, v4, v5
	v_cvt_pk_bf16_f32 v161, v6, v7
	v_cvt_pk_bf16_f32 v162, v0, v1
	v_cvt_pk_bf16_f32 v163, v2, v3
	global_store_dwordx4 v[144:145], v[160:163], off offset:256 sc1
	s_mov_b64 s[4:5], -1
	s_cbranch_vccnz .LBB0_222
	s_branch .Lip0_tail

.LBB0_970:
	s_add_i32 s101, s28, 1
	s_cmp_eq_u32 s100, s101
	s_cbranch_scc1 .Lip1_fast
	s_mov_b32 s100, s101
	v_mov_b32_e32 v153, v154
	s_mov_b64 s[30:31], s[0:1]
	s_load_dwordx2 s[30:31], s[30:31], 0x138
	v_and_or_b32 v144, v153, 15, s51
	v_lshl_add_u32 v146, s28, 8, v144
	v_ashrrev_i32_e32 v147, 31, v146
	v_lshlrev_b64 v[144:145], 6, v[146:147]
	s_waitcnt lgkmcnt(0)
	s_add_u32 s28, s30, 0xfd00000
	s_addc_u32 s29, s31, 0
	v_lshl_add_u64 v[144:145], s[28:29], 0, v[144:145]
	global_load_dwordx4 v[156:159], v[144:145], off
	global_load_dwordx4 v[160:163], v[144:145], off offset:32
	global_load_dwordx4 v[164:167], v[144:145], off offset:16
	global_load_dwordx4 v[168:171], v[144:145], off offset:48
	v_or_b32_e32 v172, 16, v146
	v_lshrrev_b32_e32 v147, 1, v153
	v_ashrrev_i32_e32 v173, 31, v172
	s_lshl_b32 s15, s59, 8
	v_lshlrev_b64 v[144:145], 6, v[172:173]
	v_and_or_b32 v147, v147, 24, s15
	v_lshl_add_u64 v[174:175], s[28:29], 0, v[144:145]
	v_or_b32_e32 v144, s52, v147
	v_ashrrev_i32_e32 v145, 31, v144
	v_lshl_add_u64 v[144:145], v[144:145], 1, s[30:31]
	v_lshl_add_u64 v[144:145], v[144:145], 0, s[12:13]
	s_andn2_b64 vcc, exec, s[4:5]
	s_waitcnt vmcnt(0)
	v_mov_b32_e32 v176, v156
	v_mov_b32_e32 v177, v160
	v_mov_b32_e32 v160, v157
	v_mov_b32_e32 v156, v158
	v_mov_b32_e32 v157, v162
	v_mov_b32_e32 v162, v159
	v_mov_b32_e32 v158, v164
	v_mov_b32_e32 v159, v168
	v_mov_b32_e32 v168, v165
	v_mov_b32_e32 v164, v166
	v_mov_b32_e32 v165, v170
	v_mov_b32_e32 v170, v167
	v_pk_add_f32 v[160:161], v[176:177], v[160:161]
	v_pk_add_f32 v[156:157], v[156:157], v[162:163]
	v_pk_add_f32 v[158:159], v[158:159], v[168:169]
	v_pk_add_f32 v[162:163], v[164:165], v[170:171]
	v_pk_add_f32 v[156:157], v[160:161], v[156:157]
	v_pk_add_f32 v[158:159], v[158:159], v[162:163]
	s_nop 0
	v_pk_add_f32 v[156:157], v[156:157], v[158:159]
	v_mad_i64_i32 v[158:159], s[30:31], v146, s58, v[144:145]
	v_add_f32_e32 v147, v156, v157
	v_fmamk_f32 v147, v147, 0x3a800000, v152
	v_rsq_f32_e32 v156, v147
	s_nop 0
	v_mov_b32_e32 v228, v156
	v_pk_mul_f32 v[126:127], v[126:127], v[156:157] op_sel_hi:[1,0]
	v_pk_mul_f32 v[124:125], v[124:125], v[156:157] op_sel_hi:[1,0]
	v_pk_mul_f32 v[122:123], v[122:123], v[156:157] op_sel_hi:[1,0]
	v_pk_mul_f32 v[120:121], v[120:121], v[156:157] op_sel_hi:[1,0]
	v_pk_mul_f32 v[118:119], v[118:119], v[156:157] op_sel_hi:[1,0]
	v_pk_mul_f32 v[116:117], v[116:117], v[156:157] op_sel_hi:[1,0]
	v_pk_mul_f32 v[160:161], v[114:115], v[156:157] op_sel_hi:[1,0]
	v_pk_mul_f32 v[156:157], v[112:113], v[156:157] op_sel_hi:[1,0]
	v_cvt_pk_bf16_f32 v112, v124, v125
	v_cvt_pk_bf16_f32 v113, v126, v127
	v_cvt_pk_bf16_f32 v114, v120, v121
	v_cvt_pk_bf16_f32 v115, v122, v123
	v_cvt_pk_bf16_f32 v116, v116, v117
	v_cvt_pk_bf16_f32 v117, v118, v119
	v_cvt_pk_bf16_f32 v118, v156, v157
	v_cvt_pk_bf16_f32 v119, v160, v161
	global_store_dwordx4 v[158:159], v[112:115], off sc1
	global_store_dwordx4 v[158:159], v[116:119], off offset:256 sc1
	global_load_dwordx4 v[112:115], v[174:175], off
	s_nop 0
	global_load_dwordx4 v[116:119], v[174:175], off offset:32
	global_load_dwordx4 v[120:123], v[174:175], off offset:16
	global_load_dwordx4 v[124:127], v[174:175], off offset:48
	v_or_b32_e32 v156, 32, v146
	v_ashrrev_i32_e32 v157, 31, v156
	v_lshlrev_b64 v[158:159], 6, v[156:157]
	s_waitcnt vmcnt(3)
	v_mov_b32_e32 v160, v112
	s_waitcnt vmcnt(2)
	v_mov_b32_e32 v161, v116
	v_mov_b32_e32 v116, v113
	v_mov_b32_e32 v112, v114
	v_mov_b32_e32 v113, v118
	v_mov_b32_e32 v118, v115
	s_waitcnt vmcnt(1)
	v_mov_b32_e32 v114, v120
	s_waitcnt vmcnt(0)
	v_mov_b32_e32 v115, v124
	v_mov_b32_e32 v124, v121
	v_mov_b32_e32 v120, v122
	v_mov_b32_e32 v121, v126
	v_mov_b32_e32 v126, v123
	v_pk_add_f32 v[116:117], v[160:161], v[116:117]
	v_pk_add_f32 v[112:113], v[112:113], v[118:119]
	v_pk_add_f32 v[114:115], v[114:115], v[124:125]
	v_pk_add_f32 v[118:119], v[120:121], v[126:127]
	v_pk_add_f32 v[112:113], v[116:117], v[112:113]
	v_pk_add_f32 v[114:115], v[114:115], v[118:119]
	v_mad_i64_i32 v[116:117], s[30:31], v172, s58, v[144:145]
	v_pk_add_f32 v[112:113], v[112:113], v[114:115]
	v_lshl_add_u64 v[114:115], s[28:29], 0, v[158:159]
	v_add_f32_e32 v112, v112, v113
	v_fmamk_f32 v112, v112, 0x3a800000, v152
	v_rsq_f32_e32 v112, v112
	s_nop 0
	v_mov_b32_e32 v229, v112
	v_pk_mul_f32 v[110:111], v[110:111], v[112:113] op_sel_hi:[1,0]
	v_pk_mul_f32 v[108:109], v[108:109], v[112:113] op_sel_hi:[1,0]
	v_pk_mul_f32 v[106:107], v[106:107], v[112:113] op_sel_hi:[1,0]
	v_pk_mul_f32 v[104:105], v[104:105], v[112:113] op_sel_hi:[1,0]
	v_pk_mul_f32 v[102:103], v[102:103], v[112:113] op_sel_hi:[1,0]
	v_pk_mul_f32 v[100:101], v[100:101], v[112:113] op_sel_hi:[1,0]
	v_pk_mul_f32 v[118:119], v[98:99], v[112:113] op_sel_hi:[1,0]
	v_pk_mul_f32 v[112:113], v[96:97], v[112:113] op_sel_hi:[1,0]
	v_cvt_pk_bf16_f32 v96, v108, v109
	v_cvt_pk_bf16_f32 v97, v110, v111
	v_cvt_pk_bf16_f32 v98, v104, v105
	v_cvt_pk_bf16_f32 v99, v106, v107
	v_cvt_pk_bf16_f32 v100, v100, v101
	v_cvt_pk_bf16_f32 v101, v102, v103
	v_cvt_pk_bf16_f32 v102, v112, v113
	v_cvt_pk_bf16_f32 v103, v118, v119
	global_store_dwordx4 v[116:117], v[96:99], off sc1
	global_store_dwordx4 v[116:117], v[100:103], off offset:256 sc1
	global_load_dwordx4 v[96:99], v[114:115], off
	s_nop 0
	global_load_dwordx4 v[100:103], v[114:115], off offset:32
	global_load_dwordx4 v[104:107], v[114:115], off offset:16
	global_load_dwordx4 v[108:111], v[114:115], off offset:48
	v_or_b32_e32 v112, 48, v146
	v_ashrrev_i32_e32 v113, 31, v112
	v_lshlrev_b64 v[114:115], 6, v[112:113]
	s_waitcnt vmcnt(3)
	v_mov_b32_e32 v116, v96
	s_waitcnt vmcnt(2)
	v_mov_b32_e32 v117, v100
	v_mov_b32_e32 v100, v97
	v_mov_b32_e32 v96, v98
	v_mov_b32_e32 v97, v102
	v_mov_b32_e32 v102, v99
	s_waitcnt vmcnt(1)
	v_mov_b32_e32 v98, v104
	s_waitcnt vmcnt(0)
	v_mov_b32_e32 v99, v108
	v_mov_b32_e32 v108, v105
	v_mov_b32_e32 v104, v106
	v_mov_b32_e32 v105, v110
	v_mov_b32_e32 v110, v107
	v_pk_add_f32 v[100:101], v[116:117], v[100:101]
	v_pk_add_f32 v[96:97], v[96:97], v[102:103]
	v_pk_add_f32 v[98:99], v[98:99], v[108:109]
	v_pk_add_f32 v[102:103], v[104:105], v[110:111]
	v_pk_add_f32 v[96:97], v[100:101], v[96:97]
	v_pk_add_f32 v[98:99], v[98:99], v[102:103]
	v_mad_i64_i32 v[100:101], s[30:31], v156, s58, v[144:145]
	v_pk_add_f32 v[96:97], v[96:97], v[98:99]
	v_lshl_add_u64 v[98:99], s[28:29], 0, v[114:115]
	v_add_f32_e32 v96, v96, v97
	v_fmamk_f32 v96, v96, 0x3a800000, v152
	v_rsq_f32_e32 v96, v96
	s_nop 0
	v_mov_b32_e32 v230, v96
	v_pk_mul_f32 v[94:95], v[94:95], v[96:97] op_sel_hi:[1,0]
	v_pk_mul_f32 v[92:93], v[92:93], v[96:97] op_sel_hi:[1,0]
	v_pk_mul_f32 v[90:91], v[90:91], v[96:97] op_sel_hi:[1,0]
	v_pk_mul_f32 v[88:89], v[88:89], v[96:97] op_sel_hi:[1,0]
	v_pk_mul_f32 v[86:87], v[86:87], v[96:97] op_sel_hi:[1,0]
	v_pk_mul_f32 v[84:85], v[84:85], v[96:97] op_sel_hi:[1,0]
	v_pk_mul_f32 v[102:103], v[82:83], v[96:97] op_sel_hi:[1,0]
	v_pk_mul_f32 v[96:97], v[80:81], v[96:97] op_sel_hi:[1,0]
	v_cvt_pk_bf16_f32 v80, v92, v93
	v_cvt_pk_bf16_f32 v81, v94, v95
	v_cvt_pk_bf16_f32 v82, v88, v89
	v_cvt_pk_bf16_f32 v83, v90, v91
	v_cvt_pk_bf16_f32 v84, v84, v85
	v_cvt_pk_bf16_f32 v85, v86, v87
	v_cvt_pk_bf16_f32 v86, v96, v97
	v_cvt_pk_bf16_f32 v87, v102, v103
	global_store_dwordx4 v[100:101], v[80:83], off sc1
	global_store_dwordx4 v[100:101], v[84:87], off offset:256 sc1
	global_load_dwordx4 v[80:83], v[98:99], off
	s_nop 0
	global_load_dwordx4 v[84:87], v[98:99], off offset:32
	global_load_dwordx4 v[88:91], v[98:99], off offset:16
	global_load_dwordx4 v[92:95], v[98:99], off offset:48
	v_add_u32_e32 v96, 0x80, v146
	v_ashrrev_i32_e32 v97, 31, v96
	v_lshlrev_b64 v[98:99], 6, v[96:97]
	s_waitcnt vmcnt(3)
	v_mov_b32_e32 v100, v80
	s_waitcnt vmcnt(2)
	v_mov_b32_e32 v101, v84
	v_mov_b32_e32 v84, v81
	v_mov_b32_e32 v80, v82
	v_mov_b32_e32 v81, v86
	v_mov_b32_e32 v86, v83
	s_waitcnt vmcnt(1)
	v_mov_b32_e32 v82, v88
	s_waitcnt vmcnt(0)
	v_mov_b32_e32 v83, v92
	v_mov_b32_e32 v92, v89
	v_mov_b32_e32 v88, v90
	v_mov_b32_e32 v89, v94
	v_mov_b32_e32 v94, v91
	v_pk_add_f32 v[84:85], v[100:101], v[84:85]
	v_pk_add_f32 v[80:81], v[80:81], v[86:87]
	v_pk_add_f32 v[82:83], v[82:83], v[92:93]
	v_pk_add_f32 v[86:87], v[88:89], v[94:95]
	v_pk_add_f32 v[80:81], v[84:85], v[80:81]
	v_pk_add_f32 v[82:83], v[82:83], v[86:87]
	v_mad_i64_i32 v[84:85], s[30:31], v112, s58, v[144:145]
	v_pk_add_f32 v[80:81], v[80:81], v[82:83]
	v_lshl_add_u64 v[82:83], s[28:29], 0, v[98:99]
	v_add_f32_e32 v80, v80, v81
	v_fmamk_f32 v80, v80, 0x3a800000, v152
	v_rsq_f32_e32 v80, v80
	s_nop 0
	v_mov_b32_e32 v231, v80
	v_pk_mul_f32 v[78:79], v[78:79], v[80:81] op_sel_hi:[1,0]
	v_pk_mul_f32 v[76:77], v[76:77], v[80:81] op_sel_hi:[1,0]
	v_pk_mul_f32 v[74:75], v[74:75], v[80:81] op_sel_hi:[1,0]
	v_pk_mul_f32 v[72:73], v[72:73], v[80:81] op_sel_hi:[1,0]
	v_pk_mul_f32 v[70:71], v[70:71], v[80:81] op_sel_hi:[1,0]
	v_pk_mul_f32 v[68:69], v[68:69], v[80:81] op_sel_hi:[1,0]
	v_pk_mul_f32 v[86:87], v[66:67], v[80:81] op_sel_hi:[1,0]
	v_pk_mul_f32 v[80:81], v[64:65], v[80:81] op_sel_hi:[1,0]
	v_cvt_pk_bf16_f32 v64, v76, v77
	v_cvt_pk_bf16_f32 v65, v78, v79
	v_cvt_pk_bf16_f32 v66, v72, v73
	v_cvt_pk_bf16_f32 v67, v74, v75
	v_cvt_pk_bf16_f32 v68, v68, v69
	v_cvt_pk_bf16_f32 v69, v70, v71
	v_cvt_pk_bf16_f32 v70, v80, v81
	v_cvt_pk_bf16_f32 v71, v86, v87
	global_store_dwordx4 v[84:85], v[64:67], off sc1
	global_store_dwordx4 v[84:85], v[68:71], off offset:256 sc1
	global_load_dwordx4 v[64:67], v[82:83], off
	s_nop 0
	global_load_dwordx4 v[68:71], v[82:83], off offset:32
	global_load_dwordx4 v[72:75], v[82:83], off offset:16
	global_load_dwordx4 v[76:79], v[82:83], off offset:48
	v_add_u32_e32 v80, 0x90, v146
	v_ashrrev_i32_e32 v81, 31, v80
	v_lshlrev_b64 v[82:83], 6, v[80:81]
	s_waitcnt vmcnt(3)
	v_mov_b32_e32 v84, v64
	s_waitcnt vmcnt(2)
	v_mov_b32_e32 v85, v68
	v_mov_b32_e32 v68, v65
	v_mov_b32_e32 v64, v66
	v_mov_b32_e32 v65, v70
	v_mov_b32_e32 v70, v67
	s_waitcnt vmcnt(1)
	v_mov_b32_e32 v66, v72
	s_waitcnt vmcnt(0)
	v_mov_b32_e32 v67, v76
	v_mov_b32_e32 v76, v73
	v_mov_b32_e32 v72, v74
	v_mov_b32_e32 v73, v78
	v_mov_b32_e32 v78, v75
	v_pk_add_f32 v[68:69], v[84:85], v[68:69]
	v_pk_add_f32 v[64:65], v[64:65], v[70:71]
	v_pk_add_f32 v[66:67], v[66:67], v[76:77]
	v_pk_add_f32 v[70:71], v[72:73], v[78:79]
	v_pk_add_f32 v[64:65], v[68:69], v[64:65]
	v_pk_add_f32 v[66:67], v[66:67], v[70:71]
	v_mad_i64_i32 v[68:69], s[30:31], v96, s58, v[144:145]
	v_pk_add_f32 v[64:65], v[64:65], v[66:67]
	v_lshl_add_u64 v[66:67], s[28:29], 0, v[82:83]
	v_add_f32_e32 v64, v64, v65
	v_fmamk_f32 v64, v64, 0x3a800000, v152
	v_rsq_f32_e32 v64, v64
	s_nop 0
	v_mov_b32_e32 v232, v64
	v_pk_mul_f32 v[62:63], v[62:63], v[64:65] op_sel_hi:[1,0]
	v_pk_mul_f32 v[60:61], v[60:61], v[64:65] op_sel_hi:[1,0]
	v_pk_mul_f32 v[58:59], v[58:59], v[64:65] op_sel_hi:[1,0]
	v_pk_mul_f32 v[56:57], v[56:57], v[64:65] op_sel_hi:[1,0]
	v_pk_mul_f32 v[54:55], v[54:55], v[64:65] op_sel_hi:[1,0]
	v_pk_mul_f32 v[52:53], v[52:53], v[64:65] op_sel_hi:[1,0]
	v_pk_mul_f32 v[70:71], v[50:51], v[64:65] op_sel_hi:[1,0]
	v_pk_mul_f32 v[64:65], v[48:49], v[64:65] op_sel_hi:[1,0]
	v_cvt_pk_bf16_f32 v48, v60, v61
	v_cvt_pk_bf16_f32 v49, v62, v63
	v_cvt_pk_bf16_f32 v50, v56, v57
	v_cvt_pk_bf16_f32 v51, v58, v59
	v_cvt_pk_bf16_f32 v52, v52, v53
	v_cvt_pk_bf16_f32 v53, v54, v55
	v_cvt_pk_bf16_f32 v54, v64, v65
	v_cvt_pk_bf16_f32 v55, v70, v71
	global_store_dwordx4 v[68:69], v[48:51], off sc1
	global_store_dwordx4 v[68:69], v[52:55], off offset:256 sc1
	global_load_dwordx4 v[48:51], v[66:67], off
	s_nop 0
	global_load_dwordx4 v[52:55], v[66:67], off offset:32
	global_load_dwordx4 v[56:59], v[66:67], off offset:16
	global_load_dwordx4 v[60:63], v[66:67], off offset:48
	v_add_u32_e32 v64, 0xa0, v146
	v_ashrrev_i32_e32 v65, 31, v64
	v_lshlrev_b64 v[66:67], 6, v[64:65]
	s_waitcnt vmcnt(3)
	v_mov_b32_e32 v68, v48
	s_waitcnt vmcnt(2)
	v_mov_b32_e32 v69, v52
	v_mov_b32_e32 v52, v49
	v_mov_b32_e32 v48, v50
	v_mov_b32_e32 v49, v54
	v_mov_b32_e32 v54, v51
	s_waitcnt vmcnt(1)
	v_mov_b32_e32 v50, v56
	s_waitcnt vmcnt(0)
	v_mov_b32_e32 v51, v60
	v_mov_b32_e32 v60, v57
	v_mov_b32_e32 v56, v58
	v_mov_b32_e32 v57, v62
	v_mov_b32_e32 v62, v59
	v_pk_add_f32 v[52:53], v[68:69], v[52:53]
	v_pk_add_f32 v[48:49], v[48:49], v[54:55]
	v_pk_add_f32 v[50:51], v[50:51], v[60:61]
	v_pk_add_f32 v[54:55], v[56:57], v[62:63]
	v_pk_add_f32 v[48:49], v[52:53], v[48:49]
	v_pk_add_f32 v[50:51], v[50:51], v[54:55]
	v_mad_i64_i32 v[52:53], s[30:31], v80, s58, v[144:145]
	v_pk_add_f32 v[48:49], v[48:49], v[50:51]
	v_lshl_add_u64 v[50:51], s[28:29], 0, v[66:67]
	v_add_f32_e32 v48, v48, v49
	v_fmamk_f32 v48, v48, 0x3a800000, v152
	v_rsq_f32_e32 v48, v48
	s_nop 0
	v_mov_b32_e32 v233, v48
	v_pk_mul_f32 v[46:47], v[46:47], v[48:49] op_sel_hi:[1,0]
	v_pk_mul_f32 v[44:45], v[44:45], v[48:49] op_sel_hi:[1,0]
	v_pk_mul_f32 v[42:43], v[42:43], v[48:49] op_sel_hi:[1,0]
	v_pk_mul_f32 v[40:41], v[40:41], v[48:49] op_sel_hi:[1,0]
	v_pk_mul_f32 v[38:39], v[38:39], v[48:49] op_sel_hi:[1,0]
	v_pk_mul_f32 v[36:37], v[36:37], v[48:49] op_sel_hi:[1,0]
	v_pk_mul_f32 v[54:55], v[34:35], v[48:49] op_sel_hi:[1,0]
	v_pk_mul_f32 v[48:49], v[32:33], v[48:49] op_sel_hi:[1,0]
	v_cvt_pk_bf16_f32 v32, v44, v45
	v_cvt_pk_bf16_f32 v33, v46, v47
	v_cvt_pk_bf16_f32 v34, v40, v41
	v_cvt_pk_bf16_f32 v35, v42, v43
	v_cvt_pk_bf16_f32 v36, v36, v37
	v_cvt_pk_bf16_f32 v37, v38, v39
	v_cvt_pk_bf16_f32 v38, v48, v49
	v_cvt_pk_bf16_f32 v39, v54, v55
	global_store_dwordx4 v[52:53], v[32:35], off sc1
	global_store_dwordx4 v[52:53], v[36:39], off offset:256 sc1
	global_load_dwordx4 v[32:35], v[50:51], off
	s_nop 0
	global_load_dwordx4 v[36:39], v[50:51], off offset:32
	global_load_dwordx4 v[40:43], v[50:51], off offset:16
	global_load_dwordx4 v[44:47], v[50:51], off offset:48
	v_add_u32_e32 v48, 0xb0, v146
	v_ashrrev_i32_e32 v49, 31, v48
	v_lshlrev_b64 v[50:51], 6, v[48:49]
	s_waitcnt vmcnt(3)
	v_mov_b32_e32 v52, v32
	s_waitcnt vmcnt(2)
	v_mov_b32_e32 v53, v36
	v_mov_b32_e32 v36, v33
	v_mov_b32_e32 v32, v34
	v_mov_b32_e32 v33, v38
	v_mov_b32_e32 v38, v35
	s_waitcnt vmcnt(1)
	v_mov_b32_e32 v34, v40
	s_waitcnt vmcnt(0)
	v_mov_b32_e32 v35, v44
	v_mov_b32_e32 v44, v41
	v_mov_b32_e32 v40, v42
	v_mov_b32_e32 v41, v46
	v_mov_b32_e32 v46, v43
	v_pk_add_f32 v[36:37], v[52:53], v[36:37]
	v_pk_add_f32 v[32:33], v[32:33], v[38:39]
	v_pk_add_f32 v[34:35], v[34:35], v[44:45]
	v_pk_add_f32 v[38:39], v[40:41], v[46:47]
	v_pk_add_f32 v[32:33], v[36:37], v[32:33]
	v_pk_add_f32 v[34:35], v[34:35], v[38:39]
	s_nop 0
	v_pk_add_f32 v[32:33], v[32:33], v[34:35]
	v_lshl_add_u64 v[34:35], s[28:29], 0, v[50:51]
	v_add_f32_e32 v32, v32, v33
	v_fmamk_f32 v32, v32, 0x3a800000, v152
	v_rsq_f32_e32 v32, v32
	v_mad_i64_i32 v[36:37], s[28:29], v64, s58, v[144:145]
	v_mov_b32_e32 v234, v32
	v_pk_mul_f32 v[30:31], v[30:31], v[32:33] op_sel_hi:[1,0]
	v_pk_mul_f32 v[28:29], v[28:29], v[32:33] op_sel_hi:[1,0]
	v_pk_mul_f32 v[26:27], v[26:27], v[32:33] op_sel_hi:[1,0]
	v_pk_mul_f32 v[24:25], v[24:25], v[32:33] op_sel_hi:[1,0]
	v_pk_mul_f32 v[22:23], v[22:23], v[32:33] op_sel_hi:[1,0]
	v_pk_mul_f32 v[20:21], v[20:21], v[32:33] op_sel_hi:[1,0]
	v_pk_mul_f32 v[38:39], v[18:19], v[32:33] op_sel_hi:[1,0]
	v_pk_mul_f32 v[32:33], v[16:17], v[32:33] op_sel_hi:[1,0]
	v_cvt_pk_bf16_f32 v16, v28, v29
	v_cvt_pk_bf16_f32 v17, v30, v31
	v_cvt_pk_bf16_f32 v18, v24, v25
	v_cvt_pk_bf16_f32 v19, v26, v27
	v_cvt_pk_bf16_f32 v20, v20, v21
	v_cvt_pk_bf16_f32 v21, v22, v23
	v_cvt_pk_bf16_f32 v22, v32, v33
	v_cvt_pk_bf16_f32 v23, v38, v39
	global_store_dwordx4 v[36:37], v[16:19], off sc1
	global_store_dwordx4 v[36:37], v[20:23], off offset:256 sc1
	global_load_dwordx4 v[16:19], v[34:35], off
	s_nop 0
	global_load_dwordx4 v[20:23], v[34:35], off offset:32
	global_load_dwordx4 v[24:27], v[34:35], off offset:16
	global_load_dwordx4 v[28:31], v[34:35], off offset:48
	s_waitcnt vmcnt(3)
	v_mov_b32_e32 v32, v16
	s_waitcnt vmcnt(2)
	v_mov_b32_e32 v33, v20
	v_mov_b32_e32 v20, v17
	v_mov_b32_e32 v16, v18
	v_mov_b32_e32 v17, v22
	v_mov_b32_e32 v22, v19
	s_waitcnt vmcnt(1)
	v_mov_b32_e32 v18, v24
	s_waitcnt vmcnt(0)
	v_mov_b32_e32 v19, v28
	v_mov_b32_e32 v28, v25
	v_mov_b32_e32 v24, v26
	v_mov_b32_e32 v25, v30
	v_mov_b32_e32 v30, v27
	v_pk_add_f32 v[20:21], v[32:33], v[20:21]
	v_pk_add_f32 v[16:17], v[16:17], v[22:23]
	v_pk_add_f32 v[18:19], v[18:19], v[28:29]
	v_pk_add_f32 v[22:23], v[24:25], v[30:31]
	v_pk_add_f32 v[16:17], v[20:21], v[16:17]
	v_pk_add_f32 v[18:19], v[18:19], v[22:23]
	s_nop 0
	v_pk_add_f32 v[16:17], v[16:17], v[18:19]
	v_mad_i64_i32 v[18:19], s[4:5], v48, s58, v[144:145]
	v_add_f32_e32 v16, v16, v17
	v_fmamk_f32 v16, v16, 0x3a800000, v152
	v_rsq_f32_e32 v16, v16
	s_mov_b64 s[4:5], -1
	v_mov_b32_e32 v235, v16
	v_pk_mul_f32 v[14:15], v[14:15], v[16:17] op_sel_hi:[1,0]
	v_pk_mul_f32 v[12:13], v[12:13], v[16:17] op_sel_hi:[1,0]
	v_pk_mul_f32 v[10:11], v[10:11], v[16:17] op_sel_hi:[1,0]
	v_pk_mul_f32 v[8:9], v[8:9], v[16:17] op_sel_hi:[1,0]
	v_pk_mul_f32 v[6:7], v[6:7], v[16:17] op_sel_hi:[1,0]
	v_pk_mul_f32 v[4:5], v[4:5], v[16:17] op_sel_hi:[1,0]
	v_pk_mul_f32 v[20:21], v[2:3], v[16:17] op_sel_hi:[1,0]
	v_pk_mul_f32 v[16:17], v[0:1], v[16:17] op_sel_hi:[1,0]
	v_cvt_pk_bf16_f32 v0, v12, v13
	v_cvt_pk_bf16_f32 v1, v14, v15
	v_cvt_pk_bf16_f32 v2, v8, v9
	v_cvt_pk_bf16_f32 v3, v10, v11
	v_cvt_pk_bf16_f32 v4, v4, v5
	v_cvt_pk_bf16_f32 v5, v6, v7
	v_cvt_pk_bf16_f32 v6, v16, v17
	v_cvt_pk_bf16_f32 v7, v20, v21
	global_store_dwordx4 v[18:19], v[0:3], off sc1
	global_store_dwordx4 v[18:19], v[4:7], off offset:256 sc1
	s_cbranch_vccnz .LBB0_963

.Lip1_fast:
	s_andn2_b64 vcc, exec, s[4:5]
	s_load_dwordx2 s[30:31], s[0:1], 0x138
	s_mov_b32 s94, 0x1e000
	s_mov_b32 s95, 0
	s_mov_b32 s96, 0x96000
	s_mov_b32 s97, 0
	v_and_or_b32 v146, v154, 15, s51
	v_lshl_add_u32 v146, s28, 8, v146
	s_lshl_b32 s101, s59, 8
	v_lshrrev_b32_e32 v144, 1, v154
	v_and_or_b32 v144, v144, 24, s101
	v_or_b32_e32 v144, s52, v144
	v_ashrrev_i32_e32 v145, 31, v144
	s_waitcnt lgkmcnt(0)
	v_lshl_add_u64 v[144:145], v[144:145], 1, s[30:31]
	v_lshl_add_u64 v[144:145], v[144:145], 0, s[12:13]
	v_mad_i64_i32 v[144:145], s[30:31], v146, s58, v[144:145]
	v_pk_mul_f32 v[124:125], v[124:125], v[228:229] op_sel_hi:[1,0]
	v_pk_mul_f32 v[126:127], v[126:127], v[228:229] op_sel_hi:[1,0]
	v_pk_mul_f32 v[120:121], v[120:121], v[228:229] op_sel_hi:[1,0]
	v_pk_mul_f32 v[122:123], v[122:123], v[228:229] op_sel_hi:[1,0]
	v_cvt_pk_bf16_f32 v156, v124, v125
	v_cvt_pk_bf16_f32 v157, v126, v127
	v_cvt_pk_bf16_f32 v158, v120, v121
	v_cvt_pk_bf16_f32 v159, v122, v123
	global_store_dwordx4 v[144:145], v[156:159], off sc1
	v_pk_mul_f32 v[116:117], v[116:117], v[228:229] op_sel_hi:[1,0]
	v_pk_mul_f32 v[118:119], v[118:119], v[228:229] op_sel_hi:[1,0]
	v_pk_mul_f32 v[112:113], v[112:113], v[228:229] op_sel_hi:[1,0]
	v_pk_mul_f32 v[114:115], v[114:115], v[228:229] op_sel_hi:[1,0]
	v_cvt_pk_bf16_f32 v160, v116, v117
	v_cvt_pk_bf16_f32 v161, v118, v119
	v_cvt_pk_bf16_f32 v162, v112, v113
	v_cvt_pk_bf16_f32 v163, v114, v115
	global_store_dwordx4 v[144:145], v[160:163], off offset:256 sc1
	v_lshl_add_u64 v[144:145], v[144:145], 0, s[94:95]
	v_pk_mul_f32 v[108:109], v[108:109], v[228:229] op_sel:[0,1] op_sel_hi:[1,1]
	v_pk_mul_f32 v[110:111], v[110:111], v[228:229] op_sel:[0,1] op_sel_hi:[1,1]
	v_pk_mul_f32 v[104:105], v[104:105], v[228:229] op_sel:[0,1] op_sel_hi:[1,1]
	v_pk_mul_f32 v[106:107], v[106:107], v[228:229] op_sel:[0,1] op_sel_hi:[1,1]
	v_cvt_pk_bf16_f32 v156, v108, v109
	v_cvt_pk_bf16_f32 v157, v110, v111
	v_cvt_pk_bf16_f32 v158, v104, v105
	v_cvt_pk_bf16_f32 v159, v106, v107
	global_store_dwordx4 v[144:145], v[156:159], off sc1
	v_pk_mul_f32 v[100:101], v[100:101], v[228:229] op_sel:[0,1] op_sel_hi:[1,1]
	v_pk_mul_f32 v[102:103], v[102:103], v[228:229] op_sel:[0,1] op_sel_hi:[1,1]
	v_pk_mul_f32 v[96:97], v[96:97], v[228:229] op_sel:[0,1] op_sel_hi:[1,1]
	v_pk_mul_f32 v[98:99], v[98:99], v[228:229] op_sel:[0,1] op_sel_hi:[1,1]
	v_cvt_pk_bf16_f32 v160, v100, v101
	v_cvt_pk_bf16_f32 v161, v102, v103
	v_cvt_pk_bf16_f32 v162, v96, v97
	v_cvt_pk_bf16_f32 v163, v98, v99
	global_store_dwordx4 v[144:145], v[160:163], off offset:256 sc1
	v_lshl_add_u64 v[144:145], v[144:145], 0, s[94:95]
	v_pk_mul_f32 v[92:93], v[92:93], v[230:231] op_sel_hi:[1,0]
	v_pk_mul_f32 v[94:95], v[94:95], v[230:231] op_sel_hi:[1,0]
	v_pk_mul_f32 v[88:89], v[88:89], v[230:231] op_sel_hi:[1,0]
	v_pk_mul_f32 v[90:91], v[90:91], v[230:231] op_sel_hi:[1,0]
	v_cvt_pk_bf16_f32 v156, v92, v93
	v_cvt_pk_bf16_f32 v157, v94, v95
	v_cvt_pk_bf16_f32 v158, v88, v89
	v_cvt_pk_bf16_f32 v159, v90, v91
	global_store_dwordx4 v[144:145], v[156:159], off sc1
	v_pk_mul_f32 v[84:85], v[84:85], v[230:231] op_sel_hi:[1,0]
	v_pk_mul_f32 v[86:87], v[86:87], v[230:231] op_sel_hi:[1,0]
	v_pk_mul_f32 v[80:81], v[80:81], v[230:231] op_sel_hi:[1,0]
	v_pk_mul_f32 v[82:83], v[82:83], v[230:231] op_sel_hi:[1,0]
	v_cvt_pk_bf16_f32 v160, v84, v85
	v_cvt_pk_bf16_f32 v161, v86, v87
	v_cvt_pk_bf16_f32 v162, v80, v81
	v_cvt_pk_bf16_f32 v163, v82, v83
	global_store_dwordx4 v[144:145], v[160:163], off offset:256 sc1
	v_lshl_add_u64 v[144:145], v[144:145], 0, s[94:95]
	v_pk_mul_f32 v[76:77], v[76:77], v[230:231] op_sel:[0,1] op_sel_hi:[1,1]
	v_pk_mul_f32 v[78:79], v[78:79], v[230:231] op_sel:[0,1] op_sel_hi:[1,1]
	v_pk_mul_f32 v[72:73], v[72:73], v[230:231] op_sel:[0,1] op_sel_hi:[1,1]
	v_pk_mul_f32 v[74:75], v[74:75], v[230:231] op_sel:[0,1] op_sel_hi:[1,1]
	v_cvt_pk_bf16_f32 v156, v76, v77
	v_cvt_pk_bf16_f32 v157, v78, v79
	v_cvt_pk_bf16_f32 v158, v72, v73
	v_cvt_pk_bf16_f32 v159, v74, v75
	global_store_dwordx4 v[144:145], v[156:159], off sc1
	v_pk_mul_f32 v[68:69], v[68:69], v[230:231] op_sel:[0,1] op_sel_hi:[1,1]
	v_pk_mul_f32 v[70:71], v[70:71], v[230:231] op_sel:[0,1] op_sel_hi:[1,1]
	v_pk_mul_f32 v[64:65], v[64:65], v[230:231] op_sel:[0,1] op_sel_hi:[1,1]
	v_pk_mul_f32 v[66:67], v[66:67], v[230:231] op_sel:[0,1] op_sel_hi:[1,1]
	v_cvt_pk_bf16_f32 v160, v68, v69
	v_cvt_pk_bf16_f32 v161, v70, v71
	v_cvt_pk_bf16_f32 v162, v64, v65
	v_cvt_pk_bf16_f32 v163, v66, v67
	global_store_dwordx4 v[144:145], v[160:163], off offset:256 sc1
	v_lshl_add_u64 v[144:145], v[144:145], 0, s[96:97]
	v_pk_mul_f32 v[60:61], v[60:61], v[232:233] op_sel_hi:[1,0]
	v_pk_mul_f32 v[62:63], v[62:63], v[232:233] op_sel_hi:[1,0]
	v_pk_mul_f32 v[56:57], v[56:57], v[232:233] op_sel_hi:[1,0]
	v_pk_mul_f32 v[58:59], v[58:59], v[232:233] op_sel_hi:[1,0]
	v_cvt_pk_bf16_f32 v156, v60, v61
	v_cvt_pk_bf16_f32 v157, v62, v63
	v_cvt_pk_bf16_f32 v158, v56, v57
	v_cvt_pk_bf16_f32 v159, v58, v59
	global_store_dwordx4 v[144:145], v[156:159], off sc1
	v_pk_mul_f32 v[52:53], v[52:53], v[232:233] op_sel_hi:[1,0]
	v_pk_mul_f32 v[54:55], v[54:55], v[232:233] op_sel_hi:[1,0]
	v_pk_mul_f32 v[48:49], v[48:49], v[232:233] op_sel_hi:[1,0]
	v_pk_mul_f32 v[50:51], v[50:51], v[232:233] op_sel_hi:[1,0]
	v_cvt_pk_bf16_f32 v160, v52, v53
	v_cvt_pk_bf16_f32 v161, v54, v55
	v_cvt_pk_bf16_f32 v162, v48, v49
	v_cvt_pk_bf16_f32 v163, v50, v51
	global_store_dwordx4 v[144:145], v[160:163], off offset:256 sc1
	v_lshl_add_u64 v[144:145], v[144:145], 0, s[94:95]
	v_pk_mul_f32 v[44:45], v[44:45], v[232:233] op_sel:[0,1] op_sel_hi:[1,1]
	v_pk_mul_f32 v[46:47], v[46:47], v[232:233] op_sel:[0,1] op_sel_hi:[1,1]
	v_pk_mul_f32 v[40:41], v[40:41], v[232:233] op_sel:[0,1] op_sel_hi:[1,1]
	v_pk_mul_f32 v[42:43], v[42:43], v[232:233] op_sel:[0,1] op_sel_hi:[1,1]
	v_cvt_pk_bf16_f32 v156, v44, v45
	v_cvt_pk_bf16_f32 v157, v46, v47
	v_cvt_pk_bf16_f32 v158, v40, v41
	v_cvt_pk_bf16_f32 v159, v42, v43
	global_store_dwordx4 v[144:145], v[156:159], off sc1
	v_pk_mul_f32 v[36:37], v[36:37], v[232:233] op_sel:[0,1] op_sel_hi:[1,1]
	v_pk_mul_f32 v[38:39], v[38:39], v[232:233] op_sel:[0,1] op_sel_hi:[1,1]
	v_pk_mul_f32 v[32:33], v[32:33], v[232:233] op_sel:[0,1] op_sel_hi:[1,1]
	v_pk_mul_f32 v[34:35], v[34:35], v[232:233] op_sel:[0,1] op_sel_hi:[1,1]
	v_cvt_pk_bf16_f32 v160, v36, v37
	v_cvt_pk_bf16_f32 v161, v38, v39
	v_cvt_pk_bf16_f32 v162, v32, v33
	v_cvt_pk_bf16_f32 v163, v34, v35
	global_store_dwordx4 v[144:145], v[160:163], off offset:256 sc1
	v_lshl_add_u64 v[144:145], v[144:145], 0, s[94:95]
	v_pk_mul_f32 v[28:29], v[28:29], v[234:235] op_sel_hi:[1,0]
	v_pk_mul_f32 v[30:31], v[30:31], v[234:235] op_sel_hi:[1,0]
	v_pk_mul_f32 v[24:25], v[24:25], v[234:235] op_sel_hi:[1,0]
	v_pk_mul_f32 v[26:27], v[26:27], v[234:235] op_sel_hi:[1,0]
	v_cvt_pk_bf16_f32 v156, v28, v29
	v_cvt_pk_bf16_f32 v157, v30, v31
	v_cvt_pk_bf16_f32 v158, v24, v25
	v_cvt_pk_bf16_f32 v159, v26, v27
	global_store_dwordx4 v[144:145], v[156:159], off sc1
	v_pk_mul_f32 v[20:21], v[20:21], v[234:235] op_sel_hi:[1,0]
	v_pk_mul_f32 v[22:23], v[22:23], v[234:235] op_sel_hi:[1,0]
	v_pk_mul_f32 v[16:17], v[16:17], v[234:235] op_sel_hi:[1,0]
	v_pk_mul_f32 v[18:19], v[18:19], v[234:235] op_sel_hi:[1,0]
	v_cvt_pk_bf16_f32 v160, v20, v21
	v_cvt_pk_bf16_f32 v161, v22, v23
	v_cvt_pk_bf16_f32 v162, v16, v17
	v_cvt_pk_bf16_f32 v163, v18, v19
	global_store_dwordx4 v[144:145], v[160:163], off offset:256 sc1
	v_lshl_add_u64 v[144:145], v[144:145], 0, s[94:95]
	v_pk_mul_f32 v[12:13], v[12:13], v[234:235] op_sel:[0,1] op_sel_hi:[1,1]
	v_pk_mul_f32 v[14:15], v[14:15], v[234:235] op_sel:[0,1] op_sel_hi:[1,1]
	v_pk_mul_f32 v[8:9], v[8:9], v[234:235] op_sel:[0,1] op_sel_hi:[1,1]
	v_pk_mul_f32 v[10:11], v[10:11], v[234:235] op_sel:[0,1] op_sel_hi:[1,1]
	v_cvt_pk_bf16_f32 v156, v12, v13
	v_cvt_pk_bf16_f32 v157, v14, v15
	v_cvt_pk_bf16_f32 v158, v8, v9
	v_cvt_pk_bf16_f32 v159, v10, v11
	global_store_dwordx4 v[144:145], v[156:159], off sc1
	v_pk_mul_f32 v[4:5], v[4:5], v[234:235] op_sel:[0,1] op_sel_hi:[1,1]
	v_pk_mul_f32 v[6:7], v[6:7], v[234:235] op_sel:[0,1] op_sel_hi:[1,1]
	v_pk_mul_f32 v[0:1], v[0:1], v[234:235] op_sel:[0,1] op_sel_hi:[1,1]
	v_pk_mul_f32 v[2:3], v[2:3], v[234:235] op_sel:[0,1] op_sel_hi:[1,1]
	v_cvt_pk_bf16_f32 v160, v4, v5
	v_cvt_pk_bf16_f32 v161, v6, v7
	v_cvt_pk_bf16_f32 v162, v0, v1
	v_cvt_pk_bf16_f32 v163, v2, v3
	global_store_dwordx4 v[144:145], v[160:163], off offset:256 sc1
	s_mov_b64 s[4:5], -1
	s_cbranch_vccnz .LBB0_963
	s_branch .Lip1_tail
